# v31 + indexer-score weight phase: all sixteen head-weight LDS reads of an iteration issued right after its MFMAs, consumed behind counted waits (four loop copies)
# baseline (speedup 1.0000x reference)
; #define LAS __attribute__((address_space(3)))
; __device__ __forceinline__ void score_item(const Frame& F, int l, int samp, int b, int c, int kc) {
;     ...
;             for (int hh = 0; hh < 8; hh += 2) {
;                 f32x16 s0, s1;
; #pragma unroll
;                 for (int i = 0; i < 16; ++i) { s0[i] = 0.f; s1[i] = 0.f; }
; #pragma unroll
;                 for (int ks = 0; ks < 4; ++ks) { const LAS unsigned char* ap = QiL + (32 * qh + rl) * 1040 + (hh * 64 + 16 * ks + 8 * h) * 2;
;                     const bf16x8 a0 = *(const LAS bf16x8*)(ap), a1 = *(const LAS bf16x8*)(ap + 128);
;                     s0 = __builtin_amdgcn_mfma_f32_32x32x16_bf16(a0, bfr[ks], s0, 0, 0, 0); s1 = __builtin_amdgcn_mfma_f32_32x32x16_bf16(a1, bfr[ks], s1, 0, 0, 0); }
; #pragma unroll
;                 for (int i = 0; i < 16; ++i) { const int q = 32 * qh + (i & 3) + 8 * (i >> 2) + 4 * h; const f32x2 w2 = *(const LAS f32x2*)(WIl + q * 8 + hh); sc[i] += w2[0] * fmaxf(s0[i], 0.f) + w2[1] * fmaxf(s1[i], 0.f); }
;             }
.LBB0_850:
	v_add_u32_e32 v107, 0, v106
	ds_read_b128 v[0:3], v107 offset:128
	ds_read_b128 v[4:7], v107
	ds_read_b128 v[108:111], v107 offset:32
	ds_read_b128 v[112:115], v107 offset:160
	ds_read_b128 v[126:129], v107 offset:64
	ds_read_b128 v[130:133], v107 offset:192
	ds_read_b128 v[134:137], v107 offset:96
	ds_read_b128 v[138:141], v107 offset:224
	s_add_i32 s11, s11, 2
	v_add_u32_e32 v106, 0x100, v106
	s_waitcnt lgkmcnt(6)
	v_mfma_f32_32x32x16_bf16 v[16:31], v[4:7], v[48:51], 0
	s_cmp_gt_u32 s11, 5
	v_mfma_f32_32x32x16_bf16 v[0:15], v[0:3], v[48:51], 0
	s_waitcnt lgkmcnt(4)
	v_mfma_f32_32x32x16_bf16 v[0:15], v[112:115], v[52:55], v[0:15]
	v_mfma_f32_32x32x16_bf16 v[16:31], v[108:111], v[52:55], v[16:31]
	s_waitcnt lgkmcnt(2)
	v_mfma_f32_32x32x16_bf16 v[0:15], v[130:133], v[56:59], v[0:15]
	v_mfma_f32_32x32x16_bf16 v[16:31], v[126:129], v[56:59], v[16:31]
	v_add_u32_e32 v107, 0, v105
	v_add_u32_e32 v105, 8, v105
	s_waitcnt lgkmcnt(0)
	v_mfma_f32_32x32x16_bf16 v[0:15], v[138:141], v[60:63], v[0:15]
	v_mfma_f32_32x32x16_bf16 v[16:31], v[134:137], v[60:63], v[16:31]
	v_add_u32_e32 v174, 0x10400, v107
	ds_read_b64 v[142:143], v174
	ds_read_b64 v[144:145], v174 offset:32
	ds_read_b64 v[146:147], v174 offset:64
	ds_read_b64 v[148:149], v174 offset:96
	ds_read_b64 v[150:151], v174 offset:256
	ds_read_b64 v[152:153], v174 offset:288
	ds_read_b64 v[154:155], v174 offset:320
	ds_read_b64 v[156:157], v174 offset:352
	ds_read_b64 v[158:159], v174 offset:512
	ds_read_b64 v[160:161], v174 offset:544
	ds_read_b64 v[162:163], v174 offset:576
	ds_read_b64 v[164:165], v174 offset:608
	ds_read_b64 v[166:167], v174 offset:768
	ds_read_b64 v[168:169], v174 offset:800
	ds_read_b64 v[170:171], v174 offset:832
	ds_read_b64 v[172:173], v174 offset:864
	v_add_u32_e32 v108, 0x10400, v107
	v_add_u32_e32 v110, 0x10420, v107
	s_nop 6
	v_max_f32_e32 v0, v0, v0
	v_max_f32_e32 v1, v1, v1
	v_max_f32_e32 v0, 0, v0
	v_max_f32_e32 v16, v16, v16
	v_max_f32_e32 v17, v17, v17
	v_max_f32_e32 v1, 0, v1
	s_waitcnt lgkmcnt(14)
	v_mov_b64_e32 v[108:109], v[142:143]
	v_mov_b64_e32 v[110:111], v[144:145]
	v_mov_b32_e32 v113, v110
	v_mov_b32_e32 v110, v109
	v_max_f32_e32 v16, 0, v16
	v_max_f32_e32 v17, 0, v17
	v_mov_b32_e32 v112, v108
	v_pk_mul_f32 v[0:1], v[0:1], v[110:111]
	v_max_f32_e32 v2, v2, v2
	v_pk_fma_f32 v[0:1], v[16:17], v[112:113], v[0:1]
	v_add_u32_e32 v17, 0x10460, v107
	v_pk_add_f32 v[100:101], v[100:101], v[0:1]
	v_add_u32_e32 v0, 0x10440, v107
	v_max_f32_e32 v3, v3, v3
	v_max_f32_e32 v16, v18, v18
	v_max_f32_e32 v2, 0, v2
	v_max_f32_e32 v17, v19, v19
	v_max_f32_e32 v3, 0, v3
	s_waitcnt lgkmcnt(12)
	v_mov_b64_e32 v[0:1], v[146:147]
	v_mov_b64_e32 v[108:109], v[148:149]
	v_mov_b32_e32 v19, v108
	v_mov_b32_e32 v108, v1
	v_max_f32_e32 v16, 0, v16
	v_max_f32_e32 v17, 0, v17
	v_mov_b32_e32 v18, v0
	v_pk_mul_f32 v[0:1], v[2:3], v[108:109]
	v_max_f32_e32 v3, v4, v4
	v_pk_fma_f32 v[0:1], v[16:17], v[18:19], v[0:1]
	v_max_f32_e32 v4, 0, v3
	v_pk_add_f32 v[98:99], v[98:99], v[0:1]
	v_add_u32_e32 v0, 0x10500, v107
	v_add_u32_e32 v3, 0x10520, v107
	v_max_f32_e32 v5, v5, v5
	v_max_f32_e32 v2, v20, v20
	v_max_f32_e32 v3, v21, v21
	v_max_f32_e32 v5, 0, v5
	s_waitcnt lgkmcnt(10)
	v_mov_b64_e32 v[0:1], v[150:151]
	v_mov_b64_e32 v[16:17], v[152:153]
	v_mov_b32_e32 v19, v16
	v_mov_b32_e32 v16, v1
	v_max_f32_e32 v2, 0, v2
	v_max_f32_e32 v3, 0, v3
	v_mov_b32_e32 v18, v0
	v_pk_mul_f32 v[0:1], v[4:5], v[16:17]
	v_max_f32_e32 v5, v7, v7
	v_pk_fma_f32 v[0:1], v[2:3], v[18:19], v[0:1]
	v_max_f32_e32 v3, v6, v6
	v_pk_add_f32 v[96:97], v[96:97], v[0:1]
	v_add_u32_e32 v0, 0x10540, v107
	v_max_f32_e32 v4, 0, v3
	v_add_u32_e32 v3, 0x10560, v107
	v_max_f32_e32 v2, v22, v22
	v_max_f32_e32 v3, v23, v23
	v_max_f32_e32 v5, 0, v5
	v_max_f32_e32 v2, 0, v2
	s_waitcnt lgkmcnt(8)
	v_mov_b64_e32 v[0:1], v[154:155]
	v_mov_b64_e32 v[16:17], v[156:157]
	v_mov_b32_e32 v7, v16
	v_mov_b32_e32 v16, v1
	v_max_f32_e32 v3, 0, v3
	v_mov_b32_e32 v6, v0
	v_pk_mul_f32 v[0:1], v[4:5], v[16:17]
	v_max_f32_e32 v5, v9, v9
	v_pk_fma_f32 v[0:1], v[2:3], v[6:7], v[0:1]
	v_max_f32_e32 v3, v8, v8
	v_pk_add_f32 v[94:95], v[94:95], v[0:1]
	v_add_u32_e32 v0, 0x10600, v107
	v_max_f32_e32 v4, 0, v3
	v_add_u32_e32 v3, 0x10620, v107
	v_max_f32_e32 v2, v24, v24
	v_max_f32_e32 v3, v25, v25
	v_max_f32_e32 v5, 0, v5
	v_max_f32_e32 v2, 0, v2
	s_waitcnt lgkmcnt(6)
	v_mov_b64_e32 v[0:1], v[158:159]
	v_mov_b64_e32 v[6:7], v[160:161]
	v_mov_b32_e32 v9, v6
	v_mov_b32_e32 v6, v1
	v_max_f32_e32 v3, 0, v3
	v_mov_b32_e32 v8, v0
	v_pk_mul_f32 v[0:1], v[4:5], v[6:7]
	v_max_f32_e32 v5, v11, v11
	v_pk_fma_f32 v[0:1], v[2:3], v[8:9], v[0:1]
	v_max_f32_e32 v3, v10, v10
	v_pk_add_f32 v[92:93], v[92:93], v[0:1]
	v_add_u32_e32 v0, 0x10640, v107
	v_max_f32_e32 v4, 0, v3
	v_add_u32_e32 v3, 0x10660, v107
	v_max_f32_e32 v2, v26, v26
	v_max_f32_e32 v3, v27, v27
	v_max_f32_e32 v5, 0, v5
	v_max_f32_e32 v2, 0, v2
	s_waitcnt lgkmcnt(4)
	v_mov_b64_e32 v[0:1], v[162:163]
	v_mov_b64_e32 v[6:7], v[164:165]
	v_mov_b32_e32 v9, v6
	v_mov_b32_e32 v6, v1
	v_max_f32_e32 v3, 0, v3
	v_mov_b32_e32 v8, v0
	v_pk_mul_f32 v[0:1], v[4:5], v[6:7]
	v_max_f32_e32 v5, v13, v13
	v_pk_fma_f32 v[0:1], v[2:3], v[8:9], v[0:1]
	v_max_f32_e32 v3, v12, v12
	v_pk_add_f32 v[90:91], v[90:91], v[0:1]
	v_add_u32_e32 v0, 0x10700, v107
	v_max_f32_e32 v4, 0, v3
	v_add_u32_e32 v3, 0x10720, v107
	v_max_f32_e32 v2, v28, v28
	v_max_f32_e32 v3, v29, v29
	v_max_f32_e32 v5, 0, v5
	v_max_f32_e32 v2, 0, v2
	s_waitcnt lgkmcnt(2)
	v_mov_b64_e32 v[0:1], v[166:167]
	v_mov_b64_e32 v[6:7], v[168:169]
	v_mov_b32_e32 v9, v6
	v_mov_b32_e32 v6, v1
	v_max_f32_e32 v3, 0, v3
	v_mov_b32_e32 v8, v0
	v_pk_mul_f32 v[0:1], v[4:5], v[6:7]
	s_nop 0
	v_pk_fma_f32 v[0:1], v[2:3], v[8:9], v[0:1]
	v_max_f32_e32 v2, v30, v30
	v_pk_add_f32 v[88:89], v[88:89], v[0:1]
	v_add_u32_e32 v0, 0x10740, v107
	v_max_f32_e32 v2, 0, v2
	s_waitcnt lgkmcnt(1)
	v_mov_b64_e32 v[0:1], v[170:171]
	v_mul_f32_e32 v0, v2, v0
	v_max_f32_e32 v2, v14, v14
	v_max_f32_e32 v2, 0, v2
	v_mul_f32_e32 v2, v2, v1
	v_add_u32_e32 v1, 0x10760, v107
	v_max_f32_e32 v1, v31, v31
	v_max_f32_e32 v6, 0, v1
	v_max_f32_e32 v1, v15, v15
	v_max_f32_e32 v7, 0, v1
	s_waitcnt lgkmcnt(0)
	v_mov_b64_e32 v[4:5], v[172:173]
	v_pk_mul_f32 v[4:5], v[6:7], v[4:5]
	s_nop 0
	v_mov_b32_e32 v1, v4
	v_mov_b32_e32 v3, v5
	v_pk_add_f32 v[0:1], v[0:1], v[2:3]
	s_nop 0
	v_pk_add_f32 v[86:87], v[86:87], v[0:1]
	s_cbranch_scc0 .LBB0_850
; __device__ __forceinline__ void score_item(const Frame& F, int l, int samp, int b, int c, int kc) {
;     ...
; #pragma unroll
;             for (int i = 0; i < 16; ++i) { const int q = 32 * qh + (i & 3) + 8 * (i >> 2) + 4 * h; __hip_atomic_store(SC + (size_t)q * 4096 + key, __float_as_uint(sc[i]), __ATOMIC_RELAXED, __HIP_MEMORY_SCOPE_AGENT); }
	v_add_u32_e32 v0, s10, v103
	v_or_b32_e32 v4, 1, v0
	v_ashrrev_i32_e32 v1, 31, v0
	v_ashrrev_i32_e32 v5, 31, v4
	v_lshlrev_b64 v[2:3], 14, v[0:1]
	v_lshlrev_b64 v[4:5], 14, v[4:5]
	v_lshl_add_u64 v[2:3], v[84:85], 0, v[2:3]
	v_lshl_add_u64 v[4:5], v[84:85], 0, v[4:5]
	global_store_dword v[2:3], v100, off sc1
	global_store_dword v[4:5], v101, off sc1
	v_or_b32_e32 v4, 2, v0
	v_or_b32_e32 v0, 3, v0
	v_ashrrev_i32_e32 v5, 31, v4
	v_ashrrev_i32_e32 v1, 31, v0
	v_lshlrev_b64 v[4:5], 14, v[4:5]
	v_lshlrev_b64 v[0:1], 14, v[0:1]
	v_lshl_add_u64 v[4:5], v[84:85], 0, v[4:5]
	v_lshl_add_u64 v[0:1], v[84:85], 0, v[0:1]
	global_store_dword v[4:5], v98, off sc1
	global_store_dword v[0:1], v99, off sc1
	v_add_co_u32_e32 v0, vcc, s92, v2
	s_mov_b32 s14, 1
	s_nop 0
	v_addc_co_u32_e32 v1, vcc, 0, v3, vcc
	global_store_dword v[0:1], v96, off sc1
	v_add_co_u32_e32 v0, vcc, s77, v2
	s_mov_b64 s[10:11], 0
	s_nop 0
	v_addc_co_u32_e32 v1, vcc, 0, v3, vcc
	global_store_dword v[0:1], v97, off sc1
	v_add_co_u32_e32 v0, vcc, s76, v2
	s_nop 1
	v_addc_co_u32_e32 v1, vcc, 0, v3, vcc
	global_store_dword v[0:1], v94, off sc1
	v_add_co_u32_e32 v0, vcc, s78, v2
	s_nop 1
	v_addc_co_u32_e32 v1, vcc, 0, v3, vcc
	global_store_dword v[0:1], v95, off sc1
	v_add_co_u32_e32 v0, vcc, s82, v2
	s_nop 1
	v_addc_co_u32_e32 v1, vcc, 0, v3, vcc
	global_store_dword v[0:1], v92, off sc1
	v_add_co_u32_e32 v0, vcc, s31, v2
	s_nop 1
	v_addc_co_u32_e32 v1, vcc, 0, v3, vcc
	global_store_dword v[0:1], v93, off sc1
	v_add_co_u32_e32 v0, vcc, s84, v2
	s_nop 1
	v_addc_co_u32_e32 v1, vcc, 0, v3, vcc
	global_store_dword v[0:1], v90, off sc1
	v_add_co_u32_e32 v0, vcc, 0x4c000, v2
	s_nop 1
	v_addc_co_u32_e32 v1, vcc, 0, v3, vcc
	global_store_dword v[0:1], v91, off sc1
	v_add_co_u32_e32 v0, vcc, s83, v2
	s_nop 1
	v_addc_co_u32_e32 v1, vcc, 0, v3, vcc
	global_store_dword v[0:1], v88, off sc1
	v_add_co_u32_e32 v0, vcc, 0x64000, v2
	s_nop 1
	v_addc_co_u32_e32 v1, vcc, 0, v3, vcc
	global_store_dword v[0:1], v89, off sc1
	v_add_co_u32_e32 v0, vcc, 0x68000, v2
	s_nop 1
	v_addc_co_u32_e32 v1, vcc, 0, v3, vcc
	global_store_dword v[0:1], v86, off sc1
	v_add_co_u32_e32 v0, vcc, 0x6c000, v2
	s_nop 1
	v_addc_co_u32_e32 v1, vcc, 0, v3, vcc
	s_and_b64 vcc, exec, s[8:9]
	global_store_dword v[0:1], v87, off sc1
	s_cbranch_vccz .LBB0_849

; #define LAS __attribute__((address_space(3)))
; __device__ __forceinline__ void score_item(const Frame& F, int l, int samp, int b, int c, int kc) {
;     ...
;             for (int hh = 0; hh < 8; hh += 2) {
;                 f32x16 s0, s1;
; #pragma unroll
;                 for (int i = 0; i < 16; ++i) { s0[i] = 0.f; s1[i] = 0.f; }
; #pragma unroll
;                 for (int ks = 0; ks < 4; ++ks) { const LAS unsigned char* ap = QiL + (32 * qh + rl) * 1040 + (hh * 64 + 16 * ks + 8 * h) * 2;
;                     const bf16x8 a0 = *(const LAS bf16x8*)(ap), a1 = *(const LAS bf16x8*)(ap + 128);
;                     s0 = __builtin_amdgcn_mfma_f32_32x32x16_bf16(a0, bfr[ks], s0, 0, 0, 0); s1 = __builtin_amdgcn_mfma_f32_32x32x16_bf16(a1, bfr[ks], s1, 0, 0, 0); }
; #pragma unroll
;                 for (int i = 0; i < 16; ++i) { const int q = 32 * qh + (i & 3) + 8 * (i >> 2) + 4 * h; const f32x2 w2 = *(const LAS f32x2*)(WIl + q * 8 + hh); sc[i] += w2[0] * fmaxf(s0[i], 0.f) + w2[1] * fmaxf(s1[i], 0.f); }
;             }
.LBB0_857:
	v_add_u32_e32 v69, 0, v68
	ds_read_b128 v[0:3], v69 offset:128
	ds_read_b128 v[4:7], v69
	ds_read_b128 v[70:73], v69 offset:32
	ds_read_b128 v[74:77], v69 offset:160
	ds_read_b128 v[126:129], v69 offset:64
	ds_read_b128 v[130:133], v69 offset:192
	ds_read_b128 v[134:137], v69 offset:96
	ds_read_b128 v[138:141], v69 offset:224
	s_add_i32 s7, s7, 2
	v_add_u32_e32 v68, 0x100, v68
	s_waitcnt lgkmcnt(6)
	v_mfma_f32_32x32x16_bf16 v[16:31], v[4:7], v[32:35], 0
	s_cmp_lt_u32 s7, 6
	v_mfma_f32_32x32x16_bf16 v[0:15], v[0:3], v[32:35], 0
	s_waitcnt lgkmcnt(4)
	v_mfma_f32_32x32x16_bf16 v[0:15], v[74:77], v[36:39], v[0:15]
	v_mfma_f32_32x32x16_bf16 v[16:31], v[70:73], v[36:39], v[16:31]
	s_waitcnt lgkmcnt(2)
	v_mfma_f32_32x32x16_bf16 v[0:15], v[130:133], v[40:43], v[0:15]
	v_mfma_f32_32x32x16_bf16 v[16:31], v[126:129], v[40:43], v[16:31]
	v_add_u32_e32 v69, 0, v67
	v_add_u32_e32 v67, 8, v67
	s_waitcnt lgkmcnt(0)
	v_mfma_f32_32x32x16_bf16 v[0:15], v[138:141], v[44:47], v[0:15]
	v_mfma_f32_32x32x16_bf16 v[16:31], v[134:137], v[44:47], v[16:31]
	v_add_u32_e32 v174, 0x10400, v69
	ds_read_b64 v[142:143], v174
	ds_read_b64 v[144:145], v174 offset:32
	ds_read_b64 v[146:147], v174 offset:64
	ds_read_b64 v[148:149], v174 offset:96
	ds_read_b64 v[150:151], v174 offset:256
	ds_read_b64 v[152:153], v174 offset:288
	ds_read_b64 v[154:155], v174 offset:320
	ds_read_b64 v[156:157], v174 offset:352
	ds_read_b64 v[158:159], v174 offset:512
	ds_read_b64 v[160:161], v174 offset:544
	ds_read_b64 v[162:163], v174 offset:576
	ds_read_b64 v[164:165], v174 offset:608
	ds_read_b64 v[166:167], v174 offset:768
	ds_read_b64 v[168:169], v174 offset:800
	ds_read_b64 v[170:171], v174 offset:832
	ds_read_b64 v[172:173], v174 offset:864
	v_add_u32_e32 v70, 0x10400, v69
	v_add_u32_e32 v72, 0x10420, v69
	s_nop 6
	v_max_f32_e32 v0, v0, v0
	v_max_f32_e32 v1, v1, v1
	v_max_f32_e32 v0, 0, v0
	v_max_f32_e32 v16, v16, v16
	v_max_f32_e32 v17, v17, v17
	v_max_f32_e32 v1, 0, v1
	s_waitcnt lgkmcnt(14)
	v_mov_b64_e32 v[70:71], v[142:143]
	v_mov_b64_e32 v[72:73], v[144:145]
	v_mov_b32_e32 v75, v72
	v_mov_b32_e32 v72, v71
	v_max_f32_e32 v16, 0, v16
	v_max_f32_e32 v17, 0, v17
	v_mov_b32_e32 v74, v70
	v_pk_mul_f32 v[0:1], v[0:1], v[72:73]
	v_max_f32_e32 v2, v2, v2
	v_pk_fma_f32 v[0:1], v[16:17], v[74:75], v[0:1]
	v_add_u32_e32 v17, 0x10460, v69
	v_pk_add_f32 v[64:65], v[64:65], v[0:1]
	v_add_u32_e32 v0, 0x10440, v69
	v_max_f32_e32 v3, v3, v3
	v_max_f32_e32 v16, v18, v18
	v_max_f32_e32 v2, 0, v2
	v_max_f32_e32 v17, v19, v19
	v_max_f32_e32 v3, 0, v3
	s_waitcnt lgkmcnt(12)
	v_mov_b64_e32 v[0:1], v[146:147]
	v_mov_b64_e32 v[70:71], v[148:149]
	v_mov_b32_e32 v19, v70
	v_mov_b32_e32 v70, v1
	v_max_f32_e32 v16, 0, v16
	v_max_f32_e32 v17, 0, v17
	v_mov_b32_e32 v18, v0
	v_pk_mul_f32 v[0:1], v[2:3], v[70:71]
	v_max_f32_e32 v3, v4, v4
	v_pk_fma_f32 v[0:1], v[16:17], v[18:19], v[0:1]
	v_max_f32_e32 v4, 0, v3
	v_pk_add_f32 v[62:63], v[62:63], v[0:1]
	v_add_u32_e32 v0, 0x10500, v69
	v_add_u32_e32 v3, 0x10520, v69
	v_max_f32_e32 v5, v5, v5
	v_max_f32_e32 v2, v20, v20
	v_max_f32_e32 v3, v21, v21
	v_max_f32_e32 v5, 0, v5
	s_waitcnt lgkmcnt(10)
	v_mov_b64_e32 v[0:1], v[150:151]
	v_mov_b64_e32 v[16:17], v[152:153]
	v_mov_b32_e32 v19, v16
	v_mov_b32_e32 v16, v1
	v_max_f32_e32 v2, 0, v2
	v_max_f32_e32 v3, 0, v3
	v_mov_b32_e32 v18, v0
	v_pk_mul_f32 v[0:1], v[4:5], v[16:17]
	v_max_f32_e32 v5, v7, v7
	v_pk_fma_f32 v[0:1], v[2:3], v[18:19], v[0:1]
	v_max_f32_e32 v3, v6, v6
	v_pk_add_f32 v[60:61], v[60:61], v[0:1]
	v_add_u32_e32 v0, 0x10540, v69
	v_max_f32_e32 v4, 0, v3
	v_add_u32_e32 v3, 0x10560, v69
	v_max_f32_e32 v2, v22, v22
	v_max_f32_e32 v3, v23, v23
	v_max_f32_e32 v5, 0, v5
	v_max_f32_e32 v2, 0, v2
	s_waitcnt lgkmcnt(8)
	v_mov_b64_e32 v[0:1], v[154:155]
	v_mov_b64_e32 v[16:17], v[156:157]
	v_mov_b32_e32 v7, v16
	v_mov_b32_e32 v16, v1
	v_max_f32_e32 v3, 0, v3
	v_mov_b32_e32 v6, v0
	v_pk_mul_f32 v[0:1], v[4:5], v[16:17]
	v_max_f32_e32 v5, v9, v9
	v_pk_fma_f32 v[0:1], v[2:3], v[6:7], v[0:1]
	v_max_f32_e32 v3, v8, v8
	v_pk_add_f32 v[58:59], v[58:59], v[0:1]
	v_add_u32_e32 v0, 0x10600, v69
	v_max_f32_e32 v4, 0, v3
	v_add_u32_e32 v3, 0x10620, v69
	v_max_f32_e32 v2, v24, v24
	v_max_f32_e32 v3, v25, v25
	v_max_f32_e32 v5, 0, v5
	v_max_f32_e32 v2, 0, v2
	s_waitcnt lgkmcnt(6)
	v_mov_b64_e32 v[0:1], v[158:159]
	v_mov_b64_e32 v[6:7], v[160:161]
	v_mov_b32_e32 v9, v6
	v_mov_b32_e32 v6, v1
	v_max_f32_e32 v3, 0, v3
	v_mov_b32_e32 v8, v0
	v_pk_mul_f32 v[0:1], v[4:5], v[6:7]
	v_max_f32_e32 v5, v11, v11
	v_pk_fma_f32 v[0:1], v[2:3], v[8:9], v[0:1]
	v_max_f32_e32 v3, v10, v10
	v_pk_add_f32 v[56:57], v[56:57], v[0:1]
	v_add_u32_e32 v0, 0x10640, v69
	v_max_f32_e32 v4, 0, v3
	v_add_u32_e32 v3, 0x10660, v69
	v_max_f32_e32 v2, v26, v26
	v_max_f32_e32 v3, v27, v27
	v_max_f32_e32 v5, 0, v5
	v_max_f32_e32 v2, 0, v2
	s_waitcnt lgkmcnt(4)
	v_mov_b64_e32 v[0:1], v[162:163]
	v_mov_b64_e32 v[6:7], v[164:165]
	v_mov_b32_e32 v9, v6
	v_mov_b32_e32 v6, v1
	v_max_f32_e32 v3, 0, v3
	v_mov_b32_e32 v8, v0
	v_pk_mul_f32 v[0:1], v[4:5], v[6:7]
	v_max_f32_e32 v5, v13, v13
	v_pk_fma_f32 v[0:1], v[2:3], v[8:9], v[0:1]
	v_max_f32_e32 v3, v12, v12
	v_pk_add_f32 v[54:55], v[54:55], v[0:1]
	v_add_u32_e32 v0, 0x10700, v69
	v_max_f32_e32 v4, 0, v3
	v_add_u32_e32 v3, 0x10720, v69
	v_max_f32_e32 v2, v28, v28
	v_max_f32_e32 v3, v29, v29
	v_max_f32_e32 v5, 0, v5
	v_max_f32_e32 v2, 0, v2
	s_waitcnt lgkmcnt(2)
	v_mov_b64_e32 v[0:1], v[166:167]
	v_mov_b64_e32 v[6:7], v[168:169]
	v_mov_b32_e32 v9, v6
	v_mov_b32_e32 v6, v1
	v_max_f32_e32 v3, 0, v3
	v_mov_b32_e32 v8, v0
	v_pk_mul_f32 v[0:1], v[4:5], v[6:7]
	s_nop 0
	v_pk_fma_f32 v[0:1], v[2:3], v[8:9], v[0:1]
	v_max_f32_e32 v2, v30, v30
	v_pk_add_f32 v[52:53], v[52:53], v[0:1]
	v_add_u32_e32 v0, 0x10740, v69
	v_max_f32_e32 v2, 0, v2
	s_waitcnt lgkmcnt(1)
	v_mov_b64_e32 v[0:1], v[170:171]
	v_mul_f32_e32 v0, v2, v0
	v_max_f32_e32 v2, v14, v14
	v_max_f32_e32 v2, 0, v2
	v_mul_f32_e32 v2, v2, v1
	v_add_u32_e32 v1, 0x10760, v69
	v_max_f32_e32 v1, v31, v31
	v_max_f32_e32 v6, 0, v1
	v_max_f32_e32 v1, v15, v15
	v_max_f32_e32 v7, 0, v1
	s_waitcnt lgkmcnt(0)
	v_mov_b64_e32 v[4:5], v[172:173]
	v_pk_mul_f32 v[4:5], v[6:7], v[4:5]
	s_nop 0
	v_mov_b32_e32 v1, v4
	v_mov_b32_e32 v3, v5
	v_pk_add_f32 v[0:1], v[0:1], v[2:3]
	s_nop 0
	v_pk_add_f32 v[50:51], v[50:51], v[0:1]
	s_cbranch_scc1 .LBB0_857
; __device__ __forceinline__ void score_item(const Frame& F, int l, int samp, int b, int c, int kc) {
;     ...
; #pragma unroll
;             for (int i = 0; i < 16; ++i) { const int q = 32 * qh + (i & 3) + 8 * (i >> 2) + 4 * h; __hip_atomic_store(SC + (size_t)q * 4096 + key, __float_as_uint(sc[i]), __ATOMIC_RELAXED, __HIP_MEMORY_SCOPE_AGENT); }
	v_add_u32_e32 v0, s6, v103
	v_or_b32_e32 v4, 1, v0
	v_ashrrev_i32_e32 v1, 31, v0
	v_ashrrev_i32_e32 v5, 31, v4
	v_lshlrev_b64 v[2:3], 14, v[0:1]
	v_lshlrev_b64 v[4:5], 14, v[4:5]
	v_lshl_add_u64 v[2:3], v[48:49], 0, v[2:3]
	v_lshl_add_u64 v[4:5], v[48:49], 0, v[4:5]
	global_store_dword v[2:3], v64, off sc1
	global_store_dword v[4:5], v65, off sc1
	v_or_b32_e32 v4, 2, v0
	v_or_b32_e32 v0, 3, v0
	v_ashrrev_i32_e32 v5, 31, v4
	v_ashrrev_i32_e32 v1, 31, v0
	v_lshlrev_b64 v[4:5], 14, v[4:5]
	v_lshlrev_b64 v[0:1], 14, v[0:1]
	v_lshl_add_u64 v[4:5], v[48:49], 0, v[4:5]
	v_lshl_add_u64 v[0:1], v[48:49], 0, v[0:1]
	global_store_dword v[4:5], v62, off sc1
	global_store_dword v[0:1], v63, off sc1
	v_add_co_u32_e32 v0, vcc, s92, v2
	s_mov_b32 s7, 1
	s_nop 0
	v_addc_co_u32_e32 v1, vcc, 0, v3, vcc
	global_store_dword v[0:1], v60, off sc1
	v_add_co_u32_e32 v0, vcc, s77, v2
	s_nop 1
	v_addc_co_u32_e32 v1, vcc, 0, v3, vcc
	global_store_dword v[0:1], v61, off sc1
	v_add_co_u32_e32 v0, vcc, s76, v2
	s_nop 1
	v_addc_co_u32_e32 v1, vcc, 0, v3, vcc
	global_store_dword v[0:1], v58, off sc1
	v_add_co_u32_e32 v0, vcc, s78, v2
	s_nop 1
	v_addc_co_u32_e32 v1, vcc, 0, v3, vcc
	global_store_dword v[0:1], v59, off sc1
	v_add_co_u32_e32 v0, vcc, s82, v2
	s_nop 1
	v_addc_co_u32_e32 v1, vcc, 0, v3, vcc
	global_store_dword v[0:1], v56, off sc1
	v_add_co_u32_e32 v0, vcc, s31, v2
	s_nop 1
	v_addc_co_u32_e32 v1, vcc, 0, v3, vcc
	global_store_dword v[0:1], v57, off sc1
	v_add_co_u32_e32 v0, vcc, s84, v2
	s_nop 1
	v_addc_co_u32_e32 v1, vcc, 0, v3, vcc
	global_store_dword v[0:1], v54, off sc1
	v_add_co_u32_e32 v0, vcc, 0x4c000, v2
	s_nop 1
	v_addc_co_u32_e32 v1, vcc, 0, v3, vcc
	global_store_dword v[0:1], v55, off sc1
	v_add_co_u32_e32 v0, vcc, s83, v2
	s_nop 1
	v_addc_co_u32_e32 v1, vcc, 0, v3, vcc
	global_store_dword v[0:1], v52, off sc1
	v_add_co_u32_e32 v0, vcc, 0x64000, v2
	s_nop 1
	v_addc_co_u32_e32 v1, vcc, 0, v3, vcc
	global_store_dword v[0:1], v53, off sc1
	v_add_co_u32_e32 v0, vcc, 0x68000, v2
	s_nop 1
	v_addc_co_u32_e32 v1, vcc, 0, v3, vcc
	global_store_dword v[0:1], v50, off sc1
	v_add_co_u32_e32 v0, vcc, 0x6c000, v2
	s_nop 1
	v_addc_co_u32_e32 v1, vcc, 0, v3, vcc
	s_andn2_b64 vcc, exec, s[4:5]
	s_mov_b64 s[4:5], 0
	global_store_dword v[0:1], v51, off sc1
	s_cbranch_vccnz .LBB0_856

; #define LAS __attribute__((address_space(3)))
; __device__ __forceinline__ void score_item(const Frame& F, int l, int samp, int b, int c, int kc) {
;     ...
;             for (int hh = 0; hh < 8; hh += 2) {
;                 f32x16 s0, s1;
; #pragma unroll
;                 for (int i = 0; i < 16; ++i) { s0[i] = 0.f; s1[i] = 0.f; }
; #pragma unroll
;                 for (int ks = 0; ks < 4; ++ks) { const LAS unsigned char* ap = QiL + (32 * qh + rl) * 1040 + (hh * 64 + 16 * ks + 8 * h) * 2;
;                     const bf16x8 a0 = *(const LAS bf16x8*)(ap), a1 = *(const LAS bf16x8*)(ap + 128);
;                     s0 = __builtin_amdgcn_mfma_f32_32x32x16_bf16(a0, bfr[ks], s0, 0, 0, 0); s1 = __builtin_amdgcn_mfma_f32_32x32x16_bf16(a1, bfr[ks], s1, 0, 0, 0); }
; #pragma unroll
;                 for (int i = 0; i < 16; ++i) { const int q = 32 * qh + (i & 3) + 8 * (i >> 2) + 4 * h; const f32x2 w2 = *(const LAS f32x2*)(WIl + q * 8 + hh); sc[i] += w2[0] * fmaxf(s0[i], 0.f) + w2[1] * fmaxf(s1[i], 0.f); }
;             }
.LBB0_872:
	v_add_u32_e32 v98, 0, v89
	ds_read_b128 v[0:3], v98 offset:128
	ds_read_b128 v[4:7], v98
	ds_read_b128 v[90:93], v98 offset:32
	ds_read_b128 v[94:97], v98 offset:160
	ds_read_b128 v[126:129], v98 offset:64
	ds_read_b128 v[130:133], v98 offset:192
	ds_read_b128 v[134:137], v98 offset:96
	ds_read_b128 v[138:141], v98 offset:224
	s_add_i32 s14, s14, 2
	v_add_u32_e32 v89, 0x100, v89
	s_waitcnt lgkmcnt(6)
	v_mfma_f32_32x32x16_bf16 v[16:31], v[4:7], v[60:63], 0
	s_cmp_gt_u32 s14, 5
	v_mfma_f32_32x32x16_bf16 v[0:15], v[0:3], v[60:63], 0
	s_waitcnt lgkmcnt(4)
	v_mfma_f32_32x32x16_bf16 v[0:15], v[94:97], v[56:59], v[0:15]
	v_mfma_f32_32x32x16_bf16 v[16:31], v[90:93], v[56:59], v[16:31]
	s_waitcnt lgkmcnt(2)
	v_mfma_f32_32x32x16_bf16 v[0:15], v[130:133], v[52:55], v[0:15]
	v_mfma_f32_32x32x16_bf16 v[16:31], v[126:129], v[52:55], v[16:31]
	s_waitcnt lgkmcnt(0)
	v_mfma_f32_32x32x16_bf16 v[0:15], v[138:141], v[48:51], v[0:15]
	v_add_u32_e32 v96, 0, v67
	v_add_u32_e32 v67, 8, v67
	v_mfma_f32_32x32x16_bf16 v[16:31], v[134:137], v[48:51], v[16:31]
	v_add_u32_e32 v174, 0x10400, v96
	ds_read_b64 v[142:143], v174
	ds_read_b64 v[144:145], v174 offset:32
	ds_read_b64 v[146:147], v174 offset:64
	ds_read_b64 v[148:149], v174 offset:96
	ds_read_b64 v[150:151], v174 offset:256
	ds_read_b64 v[152:153], v174 offset:288
	ds_read_b64 v[154:155], v174 offset:320
	ds_read_b64 v[156:157], v174 offset:352
	ds_read_b64 v[158:159], v174 offset:512
	ds_read_b64 v[160:161], v174 offset:544
	ds_read_b64 v[162:163], v174 offset:576
	ds_read_b64 v[164:165], v174 offset:608
	ds_read_b64 v[166:167], v174 offset:768
	ds_read_b64 v[168:169], v174 offset:800
	ds_read_b64 v[170:171], v174 offset:832
	ds_read_b64 v[172:173], v174 offset:864
	v_add_u32_e32 v90, 0x10400, v96
	v_add_u32_e32 v92, 0x10420, v96
	s_nop 4
	v_max_f32_e32 v0, v0, v0
	v_max_f32_e32 v1, v1, v1
	v_max_f32_e32 v0, 0, v0
	v_max_f32_e32 v16, v16, v16
	v_max_f32_e32 v17, v17, v17
	v_max_f32_e32 v1, 0, v1
	s_waitcnt lgkmcnt(14)
	v_mov_b64_e32 v[90:91], v[142:143]
	v_mov_b64_e32 v[92:93], v[144:145]
	v_mov_b32_e32 v95, v92
	v_mov_b32_e32 v92, v91
	v_max_f32_e32 v16, 0, v16
	v_max_f32_e32 v17, 0, v17
	v_mov_b32_e32 v94, v90
	v_pk_mul_f32 v[0:1], v[0:1], v[92:93]
	v_max_f32_e32 v2, v2, v2
	v_pk_fma_f32 v[0:1], v[16:17], v[94:95], v[0:1]
	v_add_u32_e32 v17, 0x10460, v96
	v_pk_add_f32 v[84:85], v[84:85], v[0:1]
	v_add_u32_e32 v0, 0x10440, v96
	v_max_f32_e32 v3, v3, v3
	v_max_f32_e32 v16, v18, v18
	v_max_f32_e32 v2, 0, v2
	v_max_f32_e32 v17, v19, v19
	v_max_f32_e32 v3, 0, v3
	s_waitcnt lgkmcnt(12)
	v_mov_b64_e32 v[0:1], v[146:147]
	v_mov_b64_e32 v[90:91], v[148:149]
	v_mov_b32_e32 v19, v90
	v_mov_b32_e32 v90, v1
	v_max_f32_e32 v16, 0, v16
	v_max_f32_e32 v17, 0, v17
	v_mov_b32_e32 v18, v0
	v_pk_mul_f32 v[0:1], v[2:3], v[90:91]
	v_max_f32_e32 v3, v4, v4
	v_pk_fma_f32 v[0:1], v[16:17], v[18:19], v[0:1]
	v_max_f32_e32 v4, 0, v3
	v_pk_add_f32 v[82:83], v[82:83], v[0:1]
	v_add_u32_e32 v0, 0x10500, v96
	v_add_u32_e32 v3, 0x10520, v96
	v_max_f32_e32 v5, v5, v5
	v_max_f32_e32 v2, v20, v20
	v_max_f32_e32 v3, v21, v21
	v_max_f32_e32 v5, 0, v5
	s_waitcnt lgkmcnt(10)
	v_mov_b64_e32 v[0:1], v[150:151]
	v_mov_b64_e32 v[16:17], v[152:153]
	v_mov_b32_e32 v19, v16
	v_mov_b32_e32 v16, v1
	v_max_f32_e32 v2, 0, v2
	v_max_f32_e32 v3, 0, v3
	v_mov_b32_e32 v18, v0
	v_pk_mul_f32 v[0:1], v[4:5], v[16:17]
	v_max_f32_e32 v5, v7, v7
	v_pk_fma_f32 v[0:1], v[2:3], v[18:19], v[0:1]
	v_max_f32_e32 v3, v6, v6
	v_pk_add_f32 v[80:81], v[80:81], v[0:1]
	v_add_u32_e32 v0, 0x10540, v96
	v_max_f32_e32 v4, 0, v3
	v_add_u32_e32 v3, 0x10560, v96
	v_max_f32_e32 v2, v22, v22
	v_max_f32_e32 v3, v23, v23
	v_max_f32_e32 v5, 0, v5
	v_max_f32_e32 v2, 0, v2
	s_waitcnt lgkmcnt(8)
	v_mov_b64_e32 v[0:1], v[154:155]
	v_mov_b64_e32 v[16:17], v[156:157]
	v_mov_b32_e32 v7, v16
	v_mov_b32_e32 v16, v1
	v_max_f32_e32 v3, 0, v3
	v_mov_b32_e32 v6, v0
	v_pk_mul_f32 v[0:1], v[4:5], v[16:17]
	v_max_f32_e32 v5, v9, v9
	v_pk_fma_f32 v[0:1], v[2:3], v[6:7], v[0:1]
	v_max_f32_e32 v3, v8, v8
	v_pk_add_f32 v[78:79], v[78:79], v[0:1]
	v_add_u32_e32 v0, 0x10600, v96
	v_max_f32_e32 v4, 0, v3
	v_add_u32_e32 v3, 0x10620, v96
	v_max_f32_e32 v2, v24, v24
	v_max_f32_e32 v3, v25, v25
	v_max_f32_e32 v5, 0, v5
	v_max_f32_e32 v2, 0, v2
	s_waitcnt lgkmcnt(6)
	v_mov_b64_e32 v[0:1], v[158:159]
	v_mov_b64_e32 v[6:7], v[160:161]
	v_mov_b32_e32 v9, v6
	v_mov_b32_e32 v6, v1
	v_max_f32_e32 v3, 0, v3
	v_mov_b32_e32 v8, v0
	v_pk_mul_f32 v[0:1], v[4:5], v[6:7]
	v_max_f32_e32 v5, v11, v11
	v_pk_fma_f32 v[0:1], v[2:3], v[8:9], v[0:1]
	v_max_f32_e32 v3, v10, v10
	v_pk_add_f32 v[76:77], v[76:77], v[0:1]
	v_add_u32_e32 v0, 0x10640, v96
	v_max_f32_e32 v4, 0, v3
	v_add_u32_e32 v3, 0x10660, v96
	v_max_f32_e32 v2, v26, v26
	v_max_f32_e32 v3, v27, v27
	v_max_f32_e32 v5, 0, v5
	v_max_f32_e32 v2, 0, v2
	s_waitcnt lgkmcnt(4)
	v_mov_b64_e32 v[0:1], v[162:163]
	v_mov_b64_e32 v[6:7], v[164:165]
	v_mov_b32_e32 v9, v6
	v_mov_b32_e32 v6, v1
	v_max_f32_e32 v3, 0, v3
	v_mov_b32_e32 v8, v0
	v_pk_mul_f32 v[0:1], v[4:5], v[6:7]
	v_max_f32_e32 v5, v13, v13
	v_pk_fma_f32 v[0:1], v[2:3], v[8:9], v[0:1]
	v_max_f32_e32 v3, v12, v12
	v_pk_add_f32 v[74:75], v[74:75], v[0:1]
	v_add_u32_e32 v0, 0x10700, v96
	v_max_f32_e32 v4, 0, v3
	v_add_u32_e32 v3, 0x10720, v96
	v_max_f32_e32 v2, v28, v28
	v_max_f32_e32 v3, v29, v29
	v_max_f32_e32 v5, 0, v5
	v_max_f32_e32 v2, 0, v2
	s_waitcnt lgkmcnt(2)
	v_mov_b64_e32 v[0:1], v[166:167]
	v_mov_b64_e32 v[6:7], v[168:169]
	v_mov_b32_e32 v9, v6
	v_mov_b32_e32 v6, v1
	v_max_f32_e32 v3, 0, v3
	v_mov_b32_e32 v8, v0
	v_pk_mul_f32 v[0:1], v[4:5], v[6:7]
	s_nop 0
	v_pk_fma_f32 v[0:1], v[2:3], v[8:9], v[0:1]
	v_max_f32_e32 v2, v30, v30
	v_pk_add_f32 v[72:73], v[72:73], v[0:1]
	v_add_u32_e32 v0, 0x10740, v96
	v_max_f32_e32 v2, 0, v2
	s_waitcnt lgkmcnt(1)
	v_mov_b64_e32 v[0:1], v[170:171]
	v_mul_f32_e32 v0, v2, v0
	v_max_f32_e32 v2, v14, v14
	v_max_f32_e32 v2, 0, v2
	v_mul_f32_e32 v2, v2, v1
	v_add_u32_e32 v1, 0x10760, v96
	v_max_f32_e32 v1, v31, v31
	v_max_f32_e32 v6, 0, v1
	v_max_f32_e32 v1, v15, v15
	v_max_f32_e32 v7, 0, v1
	s_waitcnt lgkmcnt(0)
	v_mov_b64_e32 v[4:5], v[172:173]
	v_pk_mul_f32 v[4:5], v[6:7], v[4:5]
	s_nop 0
	v_mov_b32_e32 v1, v4
	v_mov_b32_e32 v3, v5
	v_pk_add_f32 v[0:1], v[0:1], v[2:3]
	s_nop 0
	v_pk_add_f32 v[70:71], v[70:71], v[0:1]
	s_cbranch_scc0 .LBB0_872
; __device__ __forceinline__ void score_item(const Frame& F, int l, int samp, int b, int c, int kc) {
;     ...
; #pragma unroll
;             for (int i = 0; i < 16; ++i) { const int q = 32 * qh + (i & 3) + 8 * (i >> 2) + 4 * h; __hip_atomic_store(SC + (size_t)q * 4096 + key, __float_as_uint(sc[i]), __ATOMIC_RELAXED, __HIP_MEMORY_SCOPE_AGENT); }
	v_add_u32_e32 v0, s7, v87
	v_or_b32_e32 v4, 1, v0
	v_ashrrev_i32_e32 v1, 31, v0
	v_ashrrev_i32_e32 v5, 31, v4
	v_lshlrev_b64 v[2:3], 14, v[0:1]
	v_lshlrev_b64 v[4:5], 14, v[4:5]
	v_lshl_add_u64 v[2:3], v[68:69], 0, v[2:3]
	v_lshl_add_u64 v[4:5], v[68:69], 0, v[4:5]
	global_store_dword v[2:3], v84, off sc1
	global_store_dword v[4:5], v85, off sc1
	v_or_b32_e32 v4, 2, v0
	v_or_b32_e32 v0, 3, v0
	v_ashrrev_i32_e32 v5, 31, v4
	v_ashrrev_i32_e32 v1, 31, v0
	v_lshlrev_b64 v[4:5], 14, v[4:5]
	v_lshlrev_b64 v[0:1], 14, v[0:1]
	v_lshl_add_u64 v[4:5], v[68:69], 0, v[4:5]
	v_lshl_add_u64 v[0:1], v[68:69], 0, v[0:1]
	global_store_dword v[4:5], v82, off sc1
	global_store_dword v[0:1], v83, off sc1
	v_add_co_u32_e32 v0, vcc, s92, v2
	s_mov_b32 s18, 1
	s_nop 0
	v_addc_co_u32_e32 v1, vcc, 0, v3, vcc
	global_store_dword v[0:1], v80, off sc1
	v_add_co_u32_e32 v0, vcc, s77, v2
	s_mov_b64 s[14:15], 0
	s_nop 0
	v_addc_co_u32_e32 v1, vcc, 0, v3, vcc
	global_store_dword v[0:1], v81, off sc1
	v_add_co_u32_e32 v0, vcc, s76, v2
	s_nop 1
	v_addc_co_u32_e32 v1, vcc, 0, v3, vcc
	global_store_dword v[0:1], v78, off sc1
	v_add_co_u32_e32 v0, vcc, s78, v2
	s_nop 1
	v_addc_co_u32_e32 v1, vcc, 0, v3, vcc
	global_store_dword v[0:1], v79, off sc1
	v_add_co_u32_e32 v0, vcc, s82, v2
	s_nop 1
	v_addc_co_u32_e32 v1, vcc, 0, v3, vcc
	global_store_dword v[0:1], v76, off sc1
	v_add_co_u32_e32 v0, vcc, s31, v2
	s_nop 1
	v_addc_co_u32_e32 v1, vcc, 0, v3, vcc
	global_store_dword v[0:1], v77, off sc1
	v_add_co_u32_e32 v0, vcc, s84, v2
	s_nop 1
	v_addc_co_u32_e32 v1, vcc, 0, v3, vcc
	global_store_dword v[0:1], v74, off sc1
	v_add_co_u32_e32 v0, vcc, 0x4c000, v2
	s_nop 1
	v_addc_co_u32_e32 v1, vcc, 0, v3, vcc
	global_store_dword v[0:1], v75, off sc1
	v_add_co_u32_e32 v0, vcc, s83, v2
	s_nop 1
	v_addc_co_u32_e32 v1, vcc, 0, v3, vcc
	global_store_dword v[0:1], v72, off sc1
	v_add_co_u32_e32 v0, vcc, 0x64000, v2
	s_nop 1
	v_addc_co_u32_e32 v1, vcc, 0, v3, vcc
	global_store_dword v[0:1], v73, off sc1
	v_add_co_u32_e32 v0, vcc, 0x68000, v2
	s_nop 1
	v_addc_co_u32_e32 v1, vcc, 0, v3, vcc
	global_store_dword v[0:1], v70, off sc1
	v_add_co_u32_e32 v0, vcc, 0x6c000, v2
	s_nop 1
	v_addc_co_u32_e32 v1, vcc, 0, v3, vcc
	s_and_b64 vcc, exec, s[12:13]
	global_store_dword v[0:1], v71, off sc1
	s_cbranch_vccz .LBB0_871

; #define LAS __attribute__((address_space(3)))
; __device__ __forceinline__ void score_item(const Frame& F, int l, int samp, int b, int c, int kc) {
;     ...
;             for (int hh = 0; hh < 8; hh += 2) {
;                 f32x16 s0, s1;
; #pragma unroll
;                 for (int i = 0; i < 16; ++i) { s0[i] = 0.f; s1[i] = 0.f; }
; #pragma unroll
;                 for (int ks = 0; ks < 4; ++ks) { const LAS unsigned char* ap = QiL + (32 * qh + rl) * 1040 + (hh * 64 + 16 * ks + 8 * h) * 2;
;                     const bf16x8 a0 = *(const LAS bf16x8*)(ap), a1 = *(const LAS bf16x8*)(ap + 128);
;                     s0 = __builtin_amdgcn_mfma_f32_32x32x16_bf16(a0, bfr[ks], s0, 0, 0, 0); s1 = __builtin_amdgcn_mfma_f32_32x32x16_bf16(a1, bfr[ks], s1, 0, 0, 0); }
; #pragma unroll
;                 for (int i = 0; i < 16; ++i) { const int q = 32 * qh + (i & 3) + 8 * (i >> 2) + 4 * h; const f32x2 w2 = *(const LAS f32x2*)(WIl + q * 8 + hh); sc[i] += w2[0] * fmaxf(s0[i], 0.f) + w2[1] * fmaxf(s1[i], 0.f); }
;             }
.LBB0_877:
	v_add_u32_e32 v78, 0, v69
	ds_read_b128 v[0:3], v78 offset:128
	ds_read_b128 v[4:7], v78
	ds_read_b128 v[70:73], v78 offset:32
	ds_read_b128 v[74:77], v78 offset:160
	ds_read_b128 v[126:129], v78 offset:64
	ds_read_b128 v[130:133], v78 offset:192
	ds_read_b128 v[134:137], v78 offset:96
	ds_read_b128 v[138:141], v78 offset:224
	s_add_i32 s10, s10, 2
	v_add_u32_e32 v69, 0x100, v69
	s_waitcnt lgkmcnt(6)
	v_mfma_f32_32x32x16_bf16 v[16:31], v[4:7], v[44:47], 0
	s_cmp_lt_u32 s10, 6
	v_mfma_f32_32x32x16_bf16 v[0:15], v[0:3], v[44:47], 0
	s_waitcnt lgkmcnt(4)
	v_mfma_f32_32x32x16_bf16 v[0:15], v[74:77], v[40:43], v[0:15]
	v_mfma_f32_32x32x16_bf16 v[16:31], v[70:73], v[40:43], v[16:31]
	s_waitcnt lgkmcnt(2)
	v_mfma_f32_32x32x16_bf16 v[0:15], v[130:133], v[36:39], v[0:15]
	v_mfma_f32_32x32x16_bf16 v[16:31], v[126:129], v[36:39], v[16:31]
	s_waitcnt lgkmcnt(0)
	v_mfma_f32_32x32x16_bf16 v[0:15], v[138:141], v[32:35], v[0:15]
	v_add_u32_e32 v76, 0, v68
	v_add_u32_e32 v68, 8, v68
	v_mfma_f32_32x32x16_bf16 v[16:31], v[134:137], v[32:35], v[16:31]
	v_add_u32_e32 v174, 0x10400, v76
	ds_read_b64 v[142:143], v174
	ds_read_b64 v[144:145], v174 offset:32
	ds_read_b64 v[146:147], v174 offset:64
	ds_read_b64 v[148:149], v174 offset:96
	ds_read_b64 v[150:151], v174 offset:256
	ds_read_b64 v[152:153], v174 offset:288
	ds_read_b64 v[154:155], v174 offset:320
	ds_read_b64 v[156:157], v174 offset:352
	ds_read_b64 v[158:159], v174 offset:512
	ds_read_b64 v[160:161], v174 offset:544
	ds_read_b64 v[162:163], v174 offset:576
	ds_read_b64 v[164:165], v174 offset:608
	ds_read_b64 v[166:167], v174 offset:768
	ds_read_b64 v[168:169], v174 offset:800
	ds_read_b64 v[170:171], v174 offset:832
	ds_read_b64 v[172:173], v174 offset:864
	v_add_u32_e32 v70, 0x10400, v76
	v_add_u32_e32 v72, 0x10420, v76
	s_nop 4
	v_max_f32_e32 v0, v0, v0
	v_max_f32_e32 v1, v1, v1
	v_max_f32_e32 v0, 0, v0
	v_max_f32_e32 v16, v16, v16
	v_max_f32_e32 v17, v17, v17
	v_max_f32_e32 v1, 0, v1
	s_waitcnt lgkmcnt(14)
	v_mov_b64_e32 v[70:71], v[142:143]
	v_mov_b64_e32 v[72:73], v[144:145]
	v_mov_b32_e32 v75, v72
	v_mov_b32_e32 v72, v71
	v_max_f32_e32 v16, 0, v16
	v_max_f32_e32 v17, 0, v17
	v_mov_b32_e32 v74, v70
	v_pk_mul_f32 v[0:1], v[0:1], v[72:73]
	v_max_f32_e32 v2, v2, v2
	v_pk_fma_f32 v[0:1], v[16:17], v[74:75], v[0:1]
	v_add_u32_e32 v17, 0x10460, v76
	v_pk_add_f32 v[66:67], v[66:67], v[0:1]
	v_add_u32_e32 v0, 0x10440, v76
	v_max_f32_e32 v3, v3, v3
	v_max_f32_e32 v16, v18, v18
	v_max_f32_e32 v2, 0, v2
	v_max_f32_e32 v17, v19, v19
	v_max_f32_e32 v3, 0, v3
	s_waitcnt lgkmcnt(12)
	v_mov_b64_e32 v[0:1], v[146:147]
	v_mov_b64_e32 v[70:71], v[148:149]
	v_mov_b32_e32 v19, v70
	v_mov_b32_e32 v70, v1
	v_max_f32_e32 v16, 0, v16
	v_max_f32_e32 v17, 0, v17
	v_mov_b32_e32 v18, v0
	v_pk_mul_f32 v[0:1], v[2:3], v[70:71]
	v_max_f32_e32 v3, v4, v4
	v_pk_fma_f32 v[0:1], v[16:17], v[18:19], v[0:1]
	v_max_f32_e32 v4, 0, v3
	v_pk_add_f32 v[62:63], v[62:63], v[0:1]
	v_add_u32_e32 v0, 0x10500, v76
	v_add_u32_e32 v3, 0x10520, v76
	v_max_f32_e32 v5, v5, v5
	v_max_f32_e32 v2, v20, v20
	v_max_f32_e32 v3, v21, v21
	v_max_f32_e32 v5, 0, v5
	s_waitcnt lgkmcnt(10)
	v_mov_b64_e32 v[0:1], v[150:151]
	v_mov_b64_e32 v[16:17], v[152:153]
	v_mov_b32_e32 v19, v16
	v_mov_b32_e32 v16, v1
	v_max_f32_e32 v2, 0, v2
	v_max_f32_e32 v3, 0, v3
	v_mov_b32_e32 v18, v0
	v_pk_mul_f32 v[0:1], v[4:5], v[16:17]
	v_max_f32_e32 v5, v7, v7
	v_pk_fma_f32 v[0:1], v[2:3], v[18:19], v[0:1]
	v_max_f32_e32 v3, v6, v6
	v_pk_add_f32 v[60:61], v[60:61], v[0:1]
	v_add_u32_e32 v0, 0x10540, v76
	v_max_f32_e32 v4, 0, v3
	v_add_u32_e32 v3, 0x10560, v76
	v_max_f32_e32 v2, v22, v22
	v_max_f32_e32 v3, v23, v23
	v_max_f32_e32 v5, 0, v5
	v_max_f32_e32 v2, 0, v2
	s_waitcnt lgkmcnt(8)
	v_mov_b64_e32 v[0:1], v[154:155]
	v_mov_b64_e32 v[16:17], v[156:157]
	v_mov_b32_e32 v7, v16
	v_mov_b32_e32 v16, v1
	v_max_f32_e32 v3, 0, v3
	v_mov_b32_e32 v6, v0
	v_pk_mul_f32 v[0:1], v[4:5], v[16:17]
	v_max_f32_e32 v5, v9, v9
	v_pk_fma_f32 v[0:1], v[2:3], v[6:7], v[0:1]
	v_max_f32_e32 v3, v8, v8
	v_pk_add_f32 v[58:59], v[58:59], v[0:1]
	v_add_u32_e32 v0, 0x10600, v76
	v_max_f32_e32 v4, 0, v3
	v_add_u32_e32 v3, 0x10620, v76
	v_max_f32_e32 v2, v24, v24
	v_max_f32_e32 v3, v25, v25
	v_max_f32_e32 v5, 0, v5
	v_max_f32_e32 v2, 0, v2
	s_waitcnt lgkmcnt(6)
	v_mov_b64_e32 v[0:1], v[158:159]
	v_mov_b64_e32 v[6:7], v[160:161]
	v_mov_b32_e32 v9, v6
	v_mov_b32_e32 v6, v1
	v_max_f32_e32 v3, 0, v3
	v_mov_b32_e32 v8, v0
	v_pk_mul_f32 v[0:1], v[4:5], v[6:7]
	v_max_f32_e32 v5, v11, v11
	v_pk_fma_f32 v[0:1], v[2:3], v[8:9], v[0:1]
	v_max_f32_e32 v3, v10, v10
	v_pk_add_f32 v[56:57], v[56:57], v[0:1]
	v_add_u32_e32 v0, 0x10640, v76
	v_max_f32_e32 v4, 0, v3
	v_add_u32_e32 v3, 0x10660, v76
	v_max_f32_e32 v2, v26, v26
	v_max_f32_e32 v3, v27, v27
	v_max_f32_e32 v5, 0, v5
	v_max_f32_e32 v2, 0, v2
	s_waitcnt lgkmcnt(4)
	v_mov_b64_e32 v[0:1], v[162:163]
	v_mov_b64_e32 v[6:7], v[164:165]
	v_mov_b32_e32 v9, v6
	v_mov_b32_e32 v6, v1
	v_max_f32_e32 v3, 0, v3
	v_mov_b32_e32 v8, v0
	v_pk_mul_f32 v[0:1], v[4:5], v[6:7]
	v_max_f32_e32 v5, v13, v13
	v_pk_fma_f32 v[0:1], v[2:3], v[8:9], v[0:1]
	v_max_f32_e32 v3, v12, v12
	v_pk_add_f32 v[54:55], v[54:55], v[0:1]
	v_add_u32_e32 v0, 0x10700, v76
	v_max_f32_e32 v4, 0, v3
	v_add_u32_e32 v3, 0x10720, v76
	v_max_f32_e32 v2, v28, v28
	v_max_f32_e32 v3, v29, v29
	v_max_f32_e32 v5, 0, v5
	v_max_f32_e32 v2, 0, v2
	s_waitcnt lgkmcnt(2)
	v_mov_b64_e32 v[0:1], v[166:167]
	v_mov_b64_e32 v[6:7], v[168:169]
	v_mov_b32_e32 v9, v6
	v_mov_b32_e32 v6, v1
	v_max_f32_e32 v3, 0, v3
	v_mov_b32_e32 v8, v0
	v_pk_mul_f32 v[0:1], v[4:5], v[6:7]
	s_nop 0
	v_pk_fma_f32 v[0:1], v[2:3], v[8:9], v[0:1]
	v_max_f32_e32 v2, v30, v30
	v_pk_add_f32 v[52:53], v[52:53], v[0:1]
	v_add_u32_e32 v0, 0x10740, v76
	v_max_f32_e32 v2, 0, v2
	s_waitcnt lgkmcnt(1)
	v_mov_b64_e32 v[0:1], v[170:171]
	v_mul_f32_e32 v0, v2, v0
	v_max_f32_e32 v2, v14, v14
	v_max_f32_e32 v2, 0, v2
	v_mul_f32_e32 v2, v2, v1
	v_add_u32_e32 v1, 0x10760, v76
	v_max_f32_e32 v1, v31, v31
	v_max_f32_e32 v6, 0, v1
	v_max_f32_e32 v1, v15, v15
	v_max_f32_e32 v7, 0, v1
	s_waitcnt lgkmcnt(0)
	v_mov_b64_e32 v[4:5], v[172:173]
	v_pk_mul_f32 v[4:5], v[6:7], v[4:5]
	s_nop 0
	v_mov_b32_e32 v1, v4
	v_mov_b32_e32 v3, v5
	v_pk_add_f32 v[0:1], v[0:1], v[2:3]
	s_nop 0
	v_pk_add_f32 v[50:51], v[50:51], v[0:1]
	s_cbranch_scc1 .LBB0_877
; __device__ __forceinline__ void score_item(const Frame& F, int l, int samp, int b, int c, int kc) {
;     ...
; #pragma unroll
;             for (int i = 0; i < 16; ++i) { const int q = 32 * qh + (i & 3) + 8 * (i >> 2) + 4 * h; __hip_atomic_store(SC + (size_t)q * 4096 + key, __float_as_uint(sc[i]), __ATOMIC_RELAXED, __HIP_MEMORY_SCOPE_AGENT); }
	v_add_u32_e32 v0, s7, v87
	v_or_b32_e32 v4, 1, v0
	v_ashrrev_i32_e32 v1, 31, v0
	v_ashrrev_i32_e32 v5, 31, v4
	v_lshlrev_b64 v[2:3], 14, v[0:1]
	v_lshlrev_b64 v[4:5], 14, v[4:5]
	v_lshl_add_u64 v[2:3], v[48:49], 0, v[2:3]
	v_lshl_add_u64 v[4:5], v[48:49], 0, v[4:5]
	global_store_dword v[2:3], v66, off sc1
	global_store_dword v[4:5], v67, off sc1
	v_or_b32_e32 v4, 2, v0
	v_or_b32_e32 v0, 3, v0
	v_ashrrev_i32_e32 v5, 31, v4
	v_ashrrev_i32_e32 v1, 31, v0
	v_lshlrev_b64 v[4:5], 14, v[4:5]
	v_lshlrev_b64 v[0:1], 14, v[0:1]
	v_lshl_add_u64 v[4:5], v[48:49], 0, v[4:5]
	v_lshl_add_u64 v[0:1], v[48:49], 0, v[0:1]
	global_store_dword v[4:5], v62, off sc1
	global_store_dword v[0:1], v63, off sc1
	v_add_co_u32_e32 v0, vcc, s92, v2
	s_mov_b32 s10, 1
	s_nop 0
	v_addc_co_u32_e32 v1, vcc, 0, v3, vcc
	global_store_dword v[0:1], v60, off sc1
	v_add_co_u32_e32 v0, vcc, s77, v2
	s_nop 1
	v_addc_co_u32_e32 v1, vcc, 0, v3, vcc
	global_store_dword v[0:1], v61, off sc1
	v_add_co_u32_e32 v0, vcc, s76, v2
	s_nop 1
	v_addc_co_u32_e32 v1, vcc, 0, v3, vcc
	global_store_dword v[0:1], v58, off sc1
	v_add_co_u32_e32 v0, vcc, s78, v2
	s_nop 1
	v_addc_co_u32_e32 v1, vcc, 0, v3, vcc
	global_store_dword v[0:1], v59, off sc1
	v_add_co_u32_e32 v0, vcc, s82, v2
	s_nop 1
	v_addc_co_u32_e32 v1, vcc, 0, v3, vcc
	global_store_dword v[0:1], v56, off sc1
	v_add_co_u32_e32 v0, vcc, s31, v2
	s_nop 1
	v_addc_co_u32_e32 v1, vcc, 0, v3, vcc
	global_store_dword v[0:1], v57, off sc1
	v_add_co_u32_e32 v0, vcc, s84, v2
	s_nop 1
	v_addc_co_u32_e32 v1, vcc, 0, v3, vcc
	global_store_dword v[0:1], v54, off sc1
	v_add_co_u32_e32 v0, vcc, 0x4c000, v2
	s_nop 1
	v_addc_co_u32_e32 v1, vcc, 0, v3, vcc
	global_store_dword v[0:1], v55, off sc1
	v_add_co_u32_e32 v0, vcc, s83, v2
	s_nop 1
	v_addc_co_u32_e32 v1, vcc, 0, v3, vcc
	global_store_dword v[0:1], v52, off sc1
	v_add_co_u32_e32 v0, vcc, 0x64000, v2
	s_nop 1
	v_addc_co_u32_e32 v1, vcc, 0, v3, vcc
	global_store_dword v[0:1], v53, off sc1
	v_add_co_u32_e32 v0, vcc, 0x68000, v2
	s_nop 1
	v_addc_co_u32_e32 v1, vcc, 0, v3, vcc
	global_store_dword v[0:1], v50, off sc1
	v_add_co_u32_e32 v0, vcc, 0x6c000, v2
	s_nop 1
	v_addc_co_u32_e32 v1, vcc, 0, v3, vcc
	s_andn2_b64 vcc, exec, s[8:9]
	s_mov_b64 s[8:9], 0
	global_store_dword v[0:1], v51, off sc1
	s_cbranch_vccnz .LBB0_876
